# UP tile loop: next tile's rms partial sums prefetched at epilogue start, first-k-tile DMA wait deferred to k-loop entry; serialized 16-load rms chains (INPROJ header, INPROJ/UP tails) issued as one ba
# speedup vs baseline: 1.0441x; 1.0065x over previous
; DI float rstd16(const float* ssq, int m) {
;   float s = 0.f;
; #pragma unroll
;   for (int c = 0; c < 16; ++c) s += ssq[(size_t)c * TP + m];
;   return rsqrtf(s * (1.f / 1024.f) + RMS_EPS);
; }
;     ...
;   if ((EPI == EPI_UP || EPI == EPI_INPROJ) && tid < 256) rs_early = rstd16(p.ssq, m0 + tid);
.LBB0_791:
	s_cmpk_gt_u32 s95, 0x4f
	s_cselect_b64 s[10:11], -1, 0
	s_and_b64 s[14:15], s[10:11], exec
	s_cselect_b32 s14, 64, 0
	s_lshl_b32 s15, s95, 3
	s_and_b32 s15, s15, 56
	s_or_b32 s14, s15, s14
	v_readlane_b32 s15, v252, 38
	s_or_b32 s14, s14, s15
	v_mov_b32_e32 v155, v179
	s_lshl_b32 s60, s14, 8
	v_cmp_gt_i32_e64 s[40:41], s61, v155
	v_mov_b32_e32 v156, 0
	s_and_saveexec_b64 s[14:15], s[40:41]
	s_cbranch_execz .LBB0_793
	s_load_dwordx4 s[44:47], s[0:1], 0x128
	v_add_u32_e32 v2, s60, v155
	v_ashrrev_i32_e32 v3, 31, v2
	s_mov_b32 s16, 0x800000
	s_waitcnt lgkmcnt(0)
	v_lshl_add_u64 v[2:3], v[2:3], 2, s[44:45]
	s_mov_b32 s98, 0x20400
	s_mov_b32 s99, 0
	global_load_dword v204, v[2:3], off
	v_lshl_add_u64 v[2:3], v[2:3], 0, s[98:99]
	global_load_dword v205, v[2:3], off
	v_lshl_add_u64 v[2:3], v[2:3], 0, s[98:99]
	global_load_dword v206, v[2:3], off
	v_lshl_add_u64 v[2:3], v[2:3], 0, s[98:99]
	global_load_dword v207, v[2:3], off
	v_lshl_add_u64 v[2:3], v[2:3], 0, s[98:99]
	global_load_dword v208, v[2:3], off
	v_lshl_add_u64 v[2:3], v[2:3], 0, s[98:99]
	global_load_dword v209, v[2:3], off
	v_lshl_add_u64 v[2:3], v[2:3], 0, s[98:99]
	global_load_dword v210, v[2:3], off
	v_lshl_add_u64 v[2:3], v[2:3], 0, s[98:99]
	global_load_dword v211, v[2:3], off
	v_lshl_add_u64 v[2:3], v[2:3], 0, s[98:99]
	global_load_dword v212, v[2:3], off
	v_lshl_add_u64 v[2:3], v[2:3], 0, s[98:99]
	global_load_dword v213, v[2:3], off
	v_lshl_add_u64 v[2:3], v[2:3], 0, s[98:99]
	global_load_dword v214, v[2:3], off
	v_lshl_add_u64 v[2:3], v[2:3], 0, s[98:99]
	global_load_dword v215, v[2:3], off
	v_lshl_add_u64 v[2:3], v[2:3], 0, s[98:99]
	global_load_dword v216, v[2:3], off
	v_lshl_add_u64 v[2:3], v[2:3], 0, s[98:99]
	global_load_dword v217, v[2:3], off
	v_lshl_add_u64 v[2:3], v[2:3], 0, s[98:99]
	global_load_dword v218, v[2:3], off
	v_lshl_add_u64 v[2:3], v[2:3], 0, s[98:99]
	global_load_dword v219, v[2:3], off
	s_waitcnt vmcnt(0)
	v_add_f32_e32 v0, 0, v204
	v_add_f32_e32 v0, v0, v205
	v_add_f32_e32 v0, v0, v206
	v_add_f32_e32 v0, v0, v207
	v_add_f32_e32 v0, v0, v208
	v_add_f32_e32 v0, v0, v209
	v_add_f32_e32 v0, v0, v210
	v_add_f32_e32 v0, v0, v211
	v_add_f32_e32 v0, v0, v212
	v_add_f32_e32 v0, v0, v213
	v_add_f32_e32 v0, v0, v214
	v_add_f32_e32 v0, v0, v215
	v_add_f32_e32 v0, v0, v216
	v_add_f32_e32 v0, v0, v217
	v_add_f32_e32 v0, v0, v218
	v_add_f32_e32 v0, v0, v219
	v_fmamk_f32 v0, v0, 0x3a800000, v180
	v_cmp_gt_f32_e32 vcc, s16, v0
	v_mul_f32_e32 v2, 0x4b800000, v0
	s_nop 0
	v_cndmask_b32_e32 v0, v0, v2, vcc
	v_rsq_f32_e32 v0, v0
	s_nop 0
	v_mul_f32_e32 v2, 0x45800000, v0
	v_cndmask_b32_e32 v156, v0, v2, vcc

; DI float rstd16(const float* ssq, int m) {
;   float s = 0.f;
; #pragma unroll
;   for (int c = 0; c < 16; ++c) s += ssq[(size_t)c * TP + m];
;   return rsqrtf(s * (1.f / 1024.f) + RMS_EPS);
; }
;     ...
;   if ((EPI == EPI_UP || EPI == EPI_INPROJ) && tid < 256) rs_early = rstd16(p.ssq, m0 + tid);
.LBB0_1171:
	v_mov_b32_e32 v34, v179
	v_mov_b32_e32 v46, 0
	v_cmp_gt_i32_e64 s[40:41], s73, v34
	s_and_saveexec_b64 s[10:11], s[40:41]
	s_cbranch_execz .LBB0_1173
	v_ashrrev_i32_e32 v35, 31, v34
	s_waitcnt lgkmcnt(0)
	v_lshl_add_u64 v[2:3], v[34:35], 2, s[44:45]
	s_mov_b32 s14, 0x800000
	s_mov_b32 s98, 0x20000
	s_mov_b32 s99, 0
	v_lshl_add_u64 v[2:3], v[2:3], 0, s[98:99]
	s_mov_b32 s98, 0x20400
	s_mov_b32 s99, 0
	global_load_dword v204, v[2:3], off
	v_lshl_add_u64 v[2:3], v[2:3], 0, s[98:99]
	global_load_dword v205, v[2:3], off
	v_lshl_add_u64 v[2:3], v[2:3], 0, s[98:99]
	global_load_dword v206, v[2:3], off
	v_lshl_add_u64 v[2:3], v[2:3], 0, s[98:99]
	global_load_dword v207, v[2:3], off
	v_lshl_add_u64 v[2:3], v[2:3], 0, s[98:99]
	global_load_dword v208, v[2:3], off
	v_lshl_add_u64 v[2:3], v[2:3], 0, s[98:99]
	global_load_dword v209, v[2:3], off
	v_lshl_add_u64 v[2:3], v[2:3], 0, s[98:99]
	global_load_dword v210, v[2:3], off
	v_lshl_add_u64 v[2:3], v[2:3], 0, s[98:99]
	global_load_dword v211, v[2:3], off
	v_lshl_add_u64 v[2:3], v[2:3], 0, s[98:99]
	global_load_dword v212, v[2:3], off
	v_lshl_add_u64 v[2:3], v[2:3], 0, s[98:99]
	global_load_dword v213, v[2:3], off
	v_lshl_add_u64 v[2:3], v[2:3], 0, s[98:99]
	global_load_dword v214, v[2:3], off
	v_lshl_add_u64 v[2:3], v[2:3], 0, s[98:99]
	global_load_dword v215, v[2:3], off
	v_lshl_add_u64 v[2:3], v[2:3], 0, s[98:99]
	global_load_dword v216, v[2:3], off
	v_lshl_add_u64 v[2:3], v[2:3], 0, s[98:99]
	global_load_dword v217, v[2:3], off
	v_lshl_add_u64 v[2:3], v[2:3], 0, s[98:99]
	global_load_dword v218, v[2:3], off
	v_lshl_add_u64 v[2:3], v[2:3], 0, s[98:99]
	global_load_dword v219, v[2:3], off
	s_waitcnt vmcnt(0)
	v_add_f32_e32 v0, 0, v204
	v_add_f32_e32 v0, v0, v205
	v_add_f32_e32 v0, v0, v206
	v_add_f32_e32 v0, v0, v207
	v_add_f32_e32 v0, v0, v208
	v_add_f32_e32 v0, v0, v209
	v_add_f32_e32 v0, v0, v210
	v_add_f32_e32 v0, v0, v211
	v_add_f32_e32 v0, v0, v212
	v_add_f32_e32 v0, v0, v213
	v_add_f32_e32 v0, v0, v214
	v_add_f32_e32 v0, v0, v215
	v_add_f32_e32 v0, v0, v216
	v_add_f32_e32 v0, v0, v217
	v_add_f32_e32 v0, v0, v218
	v_add_f32_e32 v0, v0, v219
	v_fmamk_f32 v0, v0, 0x3a800000, v180
	v_cmp_gt_f32_e32 vcc, s14, v0
	v_mul_f32_e32 v2, 0x4b800000, v0
	s_nop 0
	v_cndmask_b32_e32 v0, v0, v2, vcc
	v_rsq_f32_e32 v0, v0
	s_nop 0
	v_mul_f32_e32 v2, 0x45800000, v0
	v_cndmask_b32_e32 v46, v0, v2, vcc

; DI float rstd16(const float* ssq, int m) {
;   float s = 0.f;
; #pragma unroll
;   for (int c = 0; c < 16; ++c) s += ssq[(size_t)c * TP + m];
;   return rsqrtf(s * (1.f / 1024.f) + RMS_EPS);
; }
; template <int MODE, int EPI, int BN>
; DI void gemm_phase(CP p, const GArgs& g, int NT, char* smem) {
;     ...
;   for (int e = j; e < total; e += nj) {
;     const int grp = e / (8 * NT);
;     const int rem = e - grp * 8 * NT;
;     const int e2 = e + nj;
;     const bool has_next = can_chain && e2 < total;
;     const int grp2 = e2 / (8 * NT), rem2 = e2 - grp2 * 8 * NT;
;     const int chain = can_chain ? ((first ? 0 : 1) | (has_next ? 2 : 0)) : 0;
;     gemm_tile<MODE, EPI, BN>(p, g, x + 8 * (grp * 8 + (rem & 7)), rem >> 3, smem, chain, x + 8 * (grp2 * 8 + (rem2 & 7)), rem2 >> 3);
.LBB0_1360:
	s_nop 0
	v_readlane_b32 s2, v252, 47
	v_readlane_b32 s3, v252, 48
	s_andn2_b64 vcc, exec, s[2:3]
	s_cbranch_vccnz .LBB0_1413
	s_load_dwordx2 s[46:47], s[0:1], 0xf8
	s_load_dwordx2 s[8:9], s[0:1], 0x108
	s_load_dwordx2 s[2:3], s[0:1], 0x118
	v_readlane_b32 s10, v252, 46
	s_cmp_eq_u32 s10, 0
	v_readlane_b32 s14, v252, 44
	s_cselect_b64 s[10:11], -1, 0
	v_readlane_b32 s15, v252, 45
	s_and_b64 s[10:11], s[14:15], s[10:11]
	s_and_b64 s[10:11], s[10:11], exec
	s_waitcnt lgkmcnt(0)
	s_cselect_b32 s49, s9, s3
	s_cselect_b32 s48, s8, s2
	v_readlane_b32 s2, v253, 25
	v_readlane_b32 s3, v253, 26
	s_andn2_b64 vcc, exec, s[2:3]
	s_cbranch_vccnz .LBB0_1376
	s_lshr_b32 s50, s94, 3
	s_add_u32 s2, s48, 0x80
	s_addc_u32 s3, s49, 0
	s_add_u32 s14, s46, 0x80
	s_addc_u32 s15, s47, 0
	s_mov_b64 s[16:17], -1
	v_readlane_b32 s51, v252, 16
	s_load_dwordx2 s[52:53], s[0:1], 0x128
	s_nop 2
	s_cmpk_gt_u32 s51, 0xaf
	s_cselect_b32 s98, 64, 0
	s_lshl_b32 s99, s51, 3
	s_and_b32 s99, s99, 56
	s_or_b32 s98, s99, s98
	s_or_b32 s98, s98, s72
	s_lshl_b32 s98, s98, 8
	s_waitcnt lgkmcnt(0)
	v_add_u32_e32 v220, s98, v179
	v_ashrrev_i32_e32 v221, 31, v220
	v_lshl_add_u64 v[220:221], v[220:221], 2, s[52:53]
	s_mov_b32 s98, 0x20400
	s_mov_b32 s99, 0
	global_load_dword v204, v[220:221], off
	v_lshl_add_u64 v[220:221], v[220:221], 0, s[98:99]
	global_load_dword v205, v[220:221], off
	v_lshl_add_u64 v[220:221], v[220:221], 0, s[98:99]
	global_load_dword v206, v[220:221], off
	v_lshl_add_u64 v[220:221], v[220:221], 0, s[98:99]
	global_load_dword v207, v[220:221], off
	v_lshl_add_u64 v[220:221], v[220:221], 0, s[98:99]
	global_load_dword v208, v[220:221], off
	v_lshl_add_u64 v[220:221], v[220:221], 0, s[98:99]
	global_load_dword v209, v[220:221], off
	v_lshl_add_u64 v[220:221], v[220:221], 0, s[98:99]
	global_load_dword v210, v[220:221], off
	v_lshl_add_u64 v[220:221], v[220:221], 0, s[98:99]
	global_load_dword v211, v[220:221], off
	v_lshl_add_u64 v[220:221], v[220:221], 0, s[98:99]
	global_load_dword v212, v[220:221], off
	v_lshl_add_u64 v[220:221], v[220:221], 0, s[98:99]
	global_load_dword v213, v[220:221], off
	v_lshl_add_u64 v[220:221], v[220:221], 0, s[98:99]
	global_load_dword v214, v[220:221], off
	v_lshl_add_u64 v[220:221], v[220:221], 0, s[98:99]
	global_load_dword v215, v[220:221], off
	v_lshl_add_u64 v[220:221], v[220:221], 0, s[98:99]
	global_load_dword v216, v[220:221], off
	v_lshl_add_u64 v[220:221], v[220:221], 0, s[98:99]
	global_load_dword v217, v[220:221], off
	v_lshl_add_u64 v[220:221], v[220:221], 0, s[98:99]
	global_load_dword v218, v[220:221], off
	v_lshl_add_u64 v[220:221], v[220:221], 0, s[98:99]
	global_load_dword v219, v[220:221], off
	s_waitcnt vmcnt(0)
	s_branch .LBB0_1364
.LBB0_1363:
	s_or_b64 exec, exec, s[16:17]
	s_cmpk_gt_u32 s51, 0xaf
	s_cselect_b32 s98, 64, 0
	s_lshl_b32 s99, s51, 3
	s_and_b32 s99, s99, 56
	s_or_b32 s98, s99, s98
	s_or_b32 s98, s98, s72
	s_lshl_b32 s98, s98, 8
	v_add_u32_e32 v220, s98, v179
	v_ashrrev_i32_e32 v221, 31, v220
	v_lshl_add_u64 v[220:221], v[220:221], 2, s[52:53]
	s_mov_b32 s98, 0x20400
	s_mov_b32 s99, 0
	global_load_dword v204, v[220:221], off
	v_lshl_add_u64 v[220:221], v[220:221], 0, s[98:99]
	global_load_dword v205, v[220:221], off
	v_lshl_add_u64 v[220:221], v[220:221], 0, s[98:99]
	global_load_dword v206, v[220:221], off
	v_lshl_add_u64 v[220:221], v[220:221], 0, s[98:99]
	global_load_dword v207, v[220:221], off
	v_lshl_add_u64 v[220:221], v[220:221], 0, s[98:99]
	global_load_dword v208, v[220:221], off
	v_lshl_add_u64 v[220:221], v[220:221], 0, s[98:99]
	global_load_dword v209, v[220:221], off
	v_lshl_add_u64 v[220:221], v[220:221], 0, s[98:99]
	global_load_dword v210, v[220:221], off
	v_lshl_add_u64 v[220:221], v[220:221], 0, s[98:99]
	global_load_dword v211, v[220:221], off
	v_lshl_add_u64 v[220:221], v[220:221], 0, s[98:99]
	global_load_dword v212, v[220:221], off
	v_lshl_add_u64 v[220:221], v[220:221], 0, s[98:99]
	global_load_dword v213, v[220:221], off
	v_lshl_add_u64 v[220:221], v[220:221], 0, s[98:99]
	global_load_dword v214, v[220:221], off
	v_lshl_add_u64 v[220:221], v[220:221], 0, s[98:99]
	global_load_dword v215, v[220:221], off
	v_lshl_add_u64 v[220:221], v[220:221], 0, s[98:99]
	global_load_dword v216, v[220:221], off
	v_lshl_add_u64 v[220:221], v[220:221], 0, s[98:99]
	global_load_dword v217, v[220:221], off
	v_lshl_add_u64 v[220:221], v[220:221], 0, s[98:99]
	global_load_dword v218, v[220:221], off
	v_lshl_add_u64 v[220:221], v[220:221], 0, s[98:99]
	global_load_dword v219, v[220:221], off
	v_lshl_add_u32 v0, v163, 6, s42
	v_lshl_add_u32 v130, v160, 7, s44
	v_or_b32_e32 v135, v130, v162
	v_ashrrev_i32_e32 v0, 1, v0
	v_lshl_or_b32 v134, v161, 2, v0
	v_subrev_u32_e32 v0, s44, v135
	s_add_i32 s16, 0, 0x24000
	v_lshl_add_u32 v0, v0, 2, s16
	v_mov_b64_e32 v[130:131], s[78:79]
	s_waitcnt lgkmcnt(0)
	s_barrier
; DI void store4(u16* dst, float a, float b, float c, float d) { *(uint2*)dst = make_uint2(pack2(a, b), pack2(c, d)); }
; DI float sigmoidf_(float x) { return __builtin_amdgcn_rcpf(1.f + __expf(-x)); }
;     ...
; #pragma unroll
;   for (int i = 0; i < MI; ++i) {
;     const int m = m0 + wm * (MI * 32) + i * 32 + l32;
;     if (EPI == EPI_UP) {
;       const float rs = rsl[m - m0];
;       const int hb0 = nw >> 1;
; #pragma unroll
;       for (int gq = 0; gq < 4; ++gq) {
;         float v[4];
; #pragma unroll
;         for (int r = 0; r < 4; ++r) {
;           float gt = acc[i][0][4 * gq + r] * rs, up = acc[i][1][4 * gq + r] * rs;
;           v[r] = gt * sigmoidf_(gt) * up;
;         }
;         int hid = hb0 + 8 * gq + 4 * hh;
;         u16* dst = hid < 1408 ? p.regB + (size_t)m * 1408 + hid : (u16*)p.out + (size_t)m * 1408 + (hid - 1408);
;         store4(dst, v[0], v[1], v[2], v[3]);
;       }
	ds_read_b32 v0, v0
	v_mad_i64_i32 v[136:137], s[40:41], v135, s29, v[130:131]
	s_load_dwordx2 s[40:41], s[0:1], 0x100
	v_or_b32_e32 v139, 32, v135
	v_or_b32_e32 v141, 64, v135
	v_or_b32_e32 v143, 0x60, v135
	v_subrev_u32_e32 v138, s44, v139
	v_subrev_u32_e32 v140, s44, v141
	v_subrev_u32_e32 v142, s44, v143
	v_lshl_add_u32 v138, v138, 2, s16
	v_lshl_add_u32 v140, v140, 2, s16
	v_lshl_add_u32 v144, v142, 2, s16
	s_waitcnt lgkmcnt(0)
	v_pk_mul_f32 v[114:115], v[114:115], v[0:1] op_sel_hi:[1,0]
	v_mov_b64_e32 v[132:133], s[40:41]
	ds_read_b32 v142, v138
	ds_read_b32 v140, v140
	ds_read_b32 v138, v144
	v_mul_f32_e32 v144, 0xbfb8aa3b, v114
	v_exp_f32_e32 v146, v144
	v_mad_i64_i32 v[144:145], s[16:17], v135, s29, v[132:133]
	v_mul_f32_e32 v135, 0xbfb8aa3b, v115
	v_pk_mul_f32 v[116:117], v[116:117], v[0:1] op_sel_hi:[1,0]
	v_exp_f32_e32 v135, v135
	v_mul_f32_e32 v147, 0xbfb8aa3b, v116
	v_exp_f32_e32 v148, v147
	v_mul_f32_e32 v147, 0xbfb8aa3b, v117
	v_exp_f32_e32 v149, v147
	v_add_f32_e32 v135, 1.0, v135
	v_add_f32_e32 v146, 1.0, v146
	v_rcp_f32_e32 v147, v135
	v_add_f32_e32 v135, 1.0, v148
	v_rcp_f32_e32 v146, v146
	v_rcp_f32_e32 v148, v135
	v_add_f32_e32 v135, 1.0, v149
	v_rcp_f32_e32 v149, v135
	v_pk_mul_f32 v[98:99], v[98:99], v[0:1] op_sel_hi:[1,0]
	v_pk_mul_f32 v[114:115], v[114:115], v[146:147]
	v_ashrrev_i32_e32 v135, 31, v134
	v_pk_mul_f32 v[114:115], v[98:99], v[114:115]
	v_pk_mul_f32 v[98:99], v[100:101], v[0:1] op_sel_hi:[1,0]
	v_pk_mul_f32 v[100:101], v[116:117], v[148:149]
	v_cvt_pk_bf16_f32 v114, v114, v115
	v_pk_mul_f32 v[116:117], v[98:99], v[100:101]
	v_lshlrev_b64 v[98:99], 1, v[134:135]
	v_mov_b32_e32 v135, v1
	v_cvt_pk_bf16_f32 v115, v116, v117
	v_pk_mul_f32 v[116:117], v[118:119], v[0:1] op_sel_hi:[1,0]
	v_lshlrev_b64 v[100:101], 1, v[134:135]
	v_mul_f32_e32 v118, 0xbfb8aa3b, v116
	v_lshl_add_u64 v[136:137], v[136:137], 0, v[100:101]
	v_exp_f32_e32 v118, v118
	v_lshl_add_u64 v[144:145], v[144:145], 0, v[98:99]
	v_lshl_add_u64 v[146:147], v[136:137], 0, s[18:19]
	v_cmp_gt_i32_e64 s[44:45], s97, v134
	v_pk_mul_f32 v[102:103], v[102:103], v[0:1] op_sel_hi:[1,0]
	v_pk_mul_f32 v[104:105], v[104:105], v[0:1] op_sel_hi:[1,0]
	v_cndmask_b32_e64 v147, v147, v145, s[44:45]
	v_cndmask_b32_e64 v146, v146, v144, s[44:45]
	global_store_dwordx2 v[146:147], v[114:115], off
	v_mul_f32_e32 v114, 0xbfb8aa3b, v117
	v_exp_f32_e32 v115, v114
	v_add_f32_e32 v114, 1.0, v118
	v_pk_mul_f32 v[118:119], v[120:121], v[0:1] op_sel_hi:[1,0]
	v_rcp_f32_e32 v114, v114
	v_mul_f32_e32 v120, 0xbfb8aa3b, v118
	v_mul_f32_e32 v121, 0xbfb8aa3b, v119
	v_exp_f32_e32 v120, v120
	v_exp_f32_e32 v121, v121
	v_add_f32_e32 v115, 1.0, v115
	v_rcp_f32_e32 v115, v115
	v_add_f32_e32 v120, 1.0, v120
	v_add_f32_e32 v121, 1.0, v121
	v_rcp_f32_e32 v120, v120
	v_rcp_f32_e32 v121, v121
	v_pk_mul_f32 v[114:115], v[116:117], v[114:115]
	v_lshl_add_u64 v[116:117], v[136:137], 0, s[20:21]
	v_pk_mul_f32 v[102:103], v[102:103], v[114:115]
	v_pk_mul_f32 v[114:115], v[118:119], v[120:121]
	v_or_b32_e32 v118, 8, v134
	v_pk_mul_f32 v[104:105], v[104:105], v[114:115]
	v_lshl_add_u64 v[114:115], v[144:145], 0, 16
	v_cmp_gt_i32_e64 s[42:43], s97, v118
	v_cvt_pk_bf16_f32 v102, v102, v103
	v_cvt_pk_bf16_f32 v103, v104, v105
	v_pk_mul_f32 v[104:105], v[122:123], v[0:1] op_sel_hi:[1,0]
	v_cndmask_b32_e64 v114, v116, v114, s[42:43]
	v_mul_f32_e32 v116, 0xbfb8aa3b, v104
	v_exp_f32_e32 v116, v116
	v_cndmask_b32_e64 v115, v117, v115, s[42:43]
	global_store_dwordx2 v[114:115], v[102:103], off
	v_mul_f32_e32 v102, 0xbfb8aa3b, v105
	v_pk_mul_f32 v[114:115], v[124:125], v[0:1] op_sel_hi:[1,0]
	v_exp_f32_e32 v103, v102
	v_add_f32_e32 v102, 1.0, v116
	v_mul_f32_e32 v116, 0xbfb8aa3b, v114
	v_mul_f32_e32 v117, 0xbfb8aa3b, v115
	v_exp_f32_e32 v116, v116
	v_exp_f32_e32 v117, v117
	v_add_f32_e32 v103, 1.0, v103
	v_rcp_f32_e32 v102, v102
	v_rcp_f32_e32 v103, v103
	v_add_f32_e32 v116, 1.0, v116
	v_add_f32_e32 v117, 1.0, v117
	v_rcp_f32_e32 v116, v116
	v_rcp_f32_e32 v117, v117
	v_pk_mul_f32 v[106:107], v[106:107], v[0:1] op_sel_hi:[1,0]
	v_pk_mul_f32 v[102:103], v[104:105], v[102:103]
	v_pk_mul_f32 v[104:105], v[108:109], v[0:1] op_sel_hi:[1,0]
	v_pk_mul_f32 v[102:103], v[106:107], v[102:103]
	v_pk_mul_f32 v[106:107], v[114:115], v[116:117]
	v_or_b32_e32 v114, 16, v134
	v_pk_mul_f32 v[104:105], v[104:105], v[106:107]
	v_lshl_add_u64 v[106:107], v[144:145], 0, 32
	v_lshl_add_u64 v[108:109], v[136:137], 0, s[36:37]
	v_cmp_gt_i32_e64 s[40:41], s97, v114
	v_cvt_pk_bf16_f32 v102, v102, v103
	v_cvt_pk_bf16_f32 v103, v104, v105
	v_pk_mul_f32 v[104:105], v[126:127], v[0:1] op_sel_hi:[1,0]
	v_cndmask_b32_e64 v106, v108, v106, s[40:41]
	v_mul_f32_e32 v108, 0xbfb8aa3b, v104
	v_exp_f32_e32 v108, v108
	v_cndmask_b32_e64 v107, v109, v107, s[40:41]
	global_store_dwordx2 v[106:107], v[102:103], off
	v_mul_f32_e32 v102, 0xbfb8aa3b, v105
	v_exp_f32_e32 v103, v102
	v_add_f32_e32 v102, 1.0, v108
	v_pk_mul_f32 v[108:109], v[128:129], v[0:1] op_sel_hi:[1,0]
	v_pk_mul_f32 v[106:107], v[110:111], v[0:1] op_sel_hi:[1,0]
	v_mul_f32_e32 v110, 0xbfb8aa3b, v108
	v_mul_f32_e32 v111, 0xbfb8aa3b, v109
	v_exp_f32_e32 v110, v110
	v_exp_f32_e32 v111, v111
	v_add_f32_e32 v103, 1.0, v103
	v_rcp_f32_e32 v102, v102
	v_rcp_f32_e32 v103, v103
	v_add_f32_e32 v110, 1.0, v110
	v_add_f32_e32 v111, 1.0, v111
	v_rcp_f32_e32 v110, v110
	v_rcp_f32_e32 v111, v111
	v_pk_mul_f32 v[102:103], v[104:105], v[102:103]
	v_pk_mul_f32 v[104:105], v[112:113], v[0:1] op_sel_hi:[1,0]
	v_pk_mul_f32 v[102:103], v[106:107], v[102:103]
	v_pk_mul_f32 v[106:107], v[108:109], v[110:111]
	v_or_b32_e32 v0, 24, v134
	v_pk_mul_f32 v[104:105], v[104:105], v[106:107]
	v_lshl_add_u64 v[106:107], v[144:145], 0, 48
	v_lshl_add_u64 v[108:109], v[136:137], 0, s[4:5]
	v_cmp_gt_i32_e32 vcc, s97, v0
	s_waitcnt lgkmcnt(2)
; DI void store4(u16* dst, float a, float b, float c, float d) { *(uint2*)dst = make_uint2(pack2(a, b), pack2(c, d)); }
; DI float sigmoidf_(float x) { return __builtin_amdgcn_rcpf(1.f + __expf(-x)); }
;     ...
; #pragma unroll
;   for (int i = 0; i < MI; ++i) {
;     const int m = m0 + wm * (MI * 32) + i * 32 + l32;
;     if (EPI == EPI_UP) {
;       const float rs = rsl[m - m0];
;       const int hb0 = nw >> 1;
; #pragma unroll
;       for (int gq = 0; gq < 4; ++gq) {
;         float v[4];
; #pragma unroll
;         for (int r = 0; r < 4; ++r) {
;           float gt = acc[i][0][4 * gq + r] * rs, up = acc[i][1][4 * gq + r] * rs;
;           v[r] = gt * sigmoidf_(gt) * up;
;         }
;         int hid = hb0 + 8 * gq + 4 * hh;
;         u16* dst = hid < 1408 ? p.regB + (size_t)m * 1408 + hid : (u16*)p.out + (size_t)m * 1408 + (hid - 1408);
;         store4(dst, v[0], v[1], v[2], v[3]);
;       }
	v_pk_mul_f32 v[82:83], v[82:83], v[142:143] op_sel_hi:[1,0]
	v_cvt_pk_bf16_f32 v102, v102, v103
	v_cndmask_b32_e32 v107, v109, v107, vcc
	v_cndmask_b32_e32 v106, v108, v106, vcc
	v_cvt_pk_bf16_f32 v103, v104, v105
	v_mul_f32_e32 v0, 0xbfb8aa3b, v82
	global_store_dwordx2 v[106:107], v[102:103], off
	v_exp_f32_e32 v0, v0
	v_mul_f32_e32 v106, 0xbfb8aa3b, v83
	v_exp_f32_e32 v107, v106
	v_pk_mul_f32 v[84:85], v[84:85], v[142:143] op_sel_hi:[1,0]
	v_add_f32_e32 v0, 1.0, v0
	v_rcp_f32_e32 v106, v0
	v_add_f32_e32 v0, 1.0, v107
	v_mul_f32_e32 v107, 0xbfb8aa3b, v84
	v_exp_f32_e32 v108, v107
	v_mul_f32_e32 v107, 0xbfb8aa3b, v85
	v_exp_f32_e32 v109, v107
	v_rcp_f32_e32 v107, v0
	v_add_f32_e32 v0, 1.0, v108
	v_rcp_f32_e32 v108, v0
	v_add_f32_e32 v0, 1.0, v109
	v_rcp_f32_e32 v109, v0
	v_pk_mul_f32 v[66:67], v[66:67], v[142:143] op_sel_hi:[1,0]
	v_pk_mul_f32 v[82:83], v[82:83], v[106:107]
	v_mad_i64_i32 v[102:103], s[16:17], v139, s29, v[130:131]
	v_pk_mul_f32 v[66:67], v[66:67], v[82:83]
	v_pk_mul_f32 v[68:69], v[68:69], v[142:143] op_sel_hi:[1,0]
	v_pk_mul_f32 v[82:83], v[84:85], v[108:109]
	v_mad_i64_i32 v[104:105], s[16:17], v139, s29, v[132:133]
	v_pk_mul_f32 v[68:69], v[68:69], v[82:83]
	v_lshl_add_u64 v[84:85], v[102:103], 0, v[100:101]
	v_lshl_add_u64 v[82:83], v[104:105], 0, v[98:99]
	v_lshl_add_u64 v[102:103], v[84:85], 0, s[18:19]
	v_cvt_pk_bf16_f32 v66, v66, v67
	v_cvt_pk_bf16_f32 v67, v68, v69
	v_pk_mul_f32 v[68:69], v[86:87], v[142:143] op_sel_hi:[1,0]
	v_cndmask_b32_e64 v103, v103, v83, s[44:45]
	v_cndmask_b32_e64 v102, v102, v82, s[44:45]
	v_mul_f32_e32 v0, 0xbfb8aa3b, v68
	v_exp_f32_e32 v0, v0
	global_store_dwordx2 v[102:103], v[66:67], off
	v_mul_f32_e32 v66, 0xbfb8aa3b, v69
	v_exp_f32_e32 v67, v66
	v_add_f32_e32 v0, 1.0, v0
	v_pk_mul_f32 v[86:87], v[88:89], v[142:143] op_sel_hi:[1,0]
	v_rcp_f32_e32 v66, v0
	v_add_f32_e32 v0, 1.0, v67
	v_mul_f32_e32 v67, 0xbfb8aa3b, v86
	v_exp_f32_e32 v88, v67
	v_mul_f32_e32 v67, 0xbfb8aa3b, v87
	v_exp_f32_e32 v89, v67
	v_rcp_f32_e32 v67, v0
	v_add_f32_e32 v0, 1.0, v88
	v_rcp_f32_e32 v88, v0
	v_add_f32_e32 v0, 1.0, v89
	v_rcp_f32_e32 v89, v0
	v_pk_mul_f32 v[70:71], v[70:71], v[142:143] op_sel_hi:[1,0]
	v_pk_mul_f32 v[66:67], v[68:69], v[66:67]
	v_pk_mul_f32 v[68:69], v[72:73], v[142:143] op_sel_hi:[1,0]
	v_pk_mul_f32 v[66:67], v[70:71], v[66:67]
	v_pk_mul_f32 v[70:71], v[86:87], v[88:89]
	v_lshl_add_u64 v[72:73], v[84:85], 0, s[20:21]
	v_pk_mul_f32 v[68:69], v[68:69], v[70:71]
	v_lshl_add_u64 v[70:71], v[82:83], 0, 16
	v_cvt_pk_bf16_f32 v66, v66, v67
	v_cvt_pk_bf16_f32 v67, v68, v69
	v_pk_mul_f32 v[68:69], v[90:91], v[142:143] op_sel_hi:[1,0]
	v_cndmask_b32_e64 v71, v73, v71, s[42:43]
	v_cndmask_b32_e64 v70, v72, v70, s[42:43]
	v_mul_f32_e32 v0, 0xbfb8aa3b, v68
	v_exp_f32_e32 v0, v0
	global_store_dwordx2 v[70:71], v[66:67], off
	v_mul_f32_e32 v66, 0xbfb8aa3b, v69
	v_exp_f32_e32 v67, v66
	v_add_f32_e32 v0, 1.0, v0
	v_pk_mul_f32 v[72:73], v[92:93], v[142:143] op_sel_hi:[1,0]
	v_rcp_f32_e32 v66, v0
	v_add_f32_e32 v0, 1.0, v67
	v_mul_f32_e32 v67, 0xbfb8aa3b, v72
	v_pk_mul_f32 v[70:71], v[74:75], v[142:143] op_sel_hi:[1,0]
	v_exp_f32_e32 v74, v67
	v_mul_f32_e32 v67, 0xbfb8aa3b, v73
	v_exp_f32_e32 v75, v67
	v_rcp_f32_e32 v67, v0
	v_add_f32_e32 v0, 1.0, v74
	v_rcp_f32_e32 v74, v0
	v_add_f32_e32 v0, 1.0, v75
	v_rcp_f32_e32 v75, v0
	v_pk_mul_f32 v[66:67], v[68:69], v[66:67]
	v_pk_mul_f32 v[68:69], v[76:77], v[142:143] op_sel_hi:[1,0]
	v_pk_mul_f32 v[66:67], v[70:71], v[66:67]
	v_pk_mul_f32 v[70:71], v[72:73], v[74:75]
	v_lshl_add_u64 v[72:73], v[84:85], 0, s[36:37]
	v_pk_mul_f32 v[68:69], v[68:69], v[70:71]
	v_lshl_add_u64 v[70:71], v[82:83], 0, 32
	v_cvt_pk_bf16_f32 v66, v66, v67
	v_cvt_pk_bf16_f32 v67, v68, v69
	v_pk_mul_f32 v[68:69], v[94:95], v[142:143] op_sel_hi:[1,0]
	v_cndmask_b32_e64 v71, v73, v71, s[40:41]
	v_cndmask_b32_e64 v70, v72, v70, s[40:41]
	v_mul_f32_e32 v0, 0xbfb8aa3b, v68
	v_exp_f32_e32 v0, v0
	global_store_dwordx2 v[70:71], v[66:67], off
	v_mul_f32_e32 v66, 0xbfb8aa3b, v69
	v_exp_f32_e32 v67, v66
	v_add_f32_e32 v0, 1.0, v0
	v_pk_mul_f32 v[72:73], v[96:97], v[142:143] op_sel_hi:[1,0]
	v_rcp_f32_e32 v66, v0
	v_add_f32_e32 v0, 1.0, v67
	v_mul_f32_e32 v67, 0xbfb8aa3b, v72
	v_exp_f32_e32 v74, v67
	v_mul_f32_e32 v67, 0xbfb8aa3b, v73
	v_exp_f32_e32 v75, v67
	v_rcp_f32_e32 v67, v0
	v_add_f32_e32 v0, 1.0, v74
	v_rcp_f32_e32 v74, v0
	v_add_f32_e32 v0, 1.0, v75
	v_rcp_f32_e32 v75, v0
	v_pk_mul_f32 v[70:71], v[78:79], v[142:143] op_sel_hi:[1,0]
	v_pk_mul_f32 v[66:67], v[68:69], v[66:67]
	v_pk_mul_f32 v[68:69], v[80:81], v[142:143] op_sel_hi:[1,0]
	v_pk_mul_f32 v[66:67], v[70:71], v[66:67]
	v_pk_mul_f32 v[70:71], v[72:73], v[74:75]
	v_lshl_add_u64 v[72:73], v[84:85], 0, s[4:5]
	v_pk_mul_f32 v[68:69], v[68:69], v[70:71]
	v_lshl_add_u64 v[70:71], v[82:83], 0, 48
	s_waitcnt lgkmcnt(1)
; DI void store4(u16* dst, float a, float b, float c, float d) { *(uint2*)dst = make_uint2(pack2(a, b), pack2(c, d)); }
; DI float sigmoidf_(float x) { return __builtin_amdgcn_rcpf(1.f + __expf(-x)); }
;     ...
; #pragma unroll
;   for (int i = 0; i < MI; ++i) {
;     const int m = m0 + wm * (MI * 32) + i * 32 + l32;
;     if (EPI == EPI_UP) {
;       const float rs = rsl[m - m0];
;       const int hb0 = nw >> 1;
; #pragma unroll
;       for (int gq = 0; gq < 4; ++gq) {
;         float v[4];
; #pragma unroll
;         for (int r = 0; r < 4; ++r) {
;           float gt = acc[i][0][4 * gq + r] * rs, up = acc[i][1][4 * gq + r] * rs;
;           v[r] = gt * sigmoidf_(gt) * up;
;         }
;         int hid = hb0 + 8 * gq + 4 * hh;
;         u16* dst = hid < 1408 ? p.regB + (size_t)m * 1408 + hid : (u16*)p.out + (size_t)m * 1408 + (hid - 1408);
;         store4(dst, v[0], v[1], v[2], v[3]);
;       }
	v_pk_mul_f32 v[50:51], v[50:51], v[140:141] op_sel_hi:[1,0]
	v_cndmask_b32_e32 v71, v73, v71, vcc
	v_cndmask_b32_e32 v70, v72, v70, vcc
	v_cvt_pk_bf16_f32 v66, v66, v67
	v_cvt_pk_bf16_f32 v67, v68, v69
	v_mul_f32_e32 v0, 0xbfb8aa3b, v50
	global_store_dwordx2 v[70:71], v[66:67], off
	v_exp_f32_e32 v0, v0
	v_mul_f32_e32 v70, 0xbfb8aa3b, v51
	v_exp_f32_e32 v71, v70
	v_pk_mul_f32 v[52:53], v[52:53], v[140:141] op_sel_hi:[1,0]
	v_add_f32_e32 v0, 1.0, v0
	v_rcp_f32_e32 v70, v0
	v_add_f32_e32 v0, 1.0, v71
	v_mul_f32_e32 v71, 0xbfb8aa3b, v52
	v_exp_f32_e32 v72, v71
	v_mul_f32_e32 v71, 0xbfb8aa3b, v53
	v_exp_f32_e32 v73, v71
	v_rcp_f32_e32 v71, v0
	v_add_f32_e32 v0, 1.0, v72
	v_rcp_f32_e32 v72, v0
	v_add_f32_e32 v0, 1.0, v73
	v_rcp_f32_e32 v73, v0
	v_pk_mul_f32 v[34:35], v[34:35], v[140:141] op_sel_hi:[1,0]
	v_pk_mul_f32 v[50:51], v[50:51], v[70:71]
	v_mad_i64_i32 v[66:67], s[16:17], v141, s29, v[130:131]
	v_pk_mul_f32 v[34:35], v[34:35], v[50:51]
	v_pk_mul_f32 v[36:37], v[36:37], v[140:141] op_sel_hi:[1,0]
	v_pk_mul_f32 v[50:51], v[52:53], v[72:73]
	v_mad_i64_i32 v[68:69], s[16:17], v141, s29, v[132:133]
	v_pk_mul_f32 v[36:37], v[36:37], v[50:51]
	v_lshl_add_u64 v[52:53], v[66:67], 0, v[100:101]
	v_lshl_add_u64 v[50:51], v[68:69], 0, v[98:99]
	v_lshl_add_u64 v[66:67], v[52:53], 0, s[18:19]
	v_cvt_pk_bf16_f32 v34, v34, v35
	v_cvt_pk_bf16_f32 v35, v36, v37
	v_pk_mul_f32 v[36:37], v[54:55], v[140:141] op_sel_hi:[1,0]
	v_cndmask_b32_e64 v67, v67, v51, s[44:45]
	v_cndmask_b32_e64 v66, v66, v50, s[44:45]
	v_mul_f32_e32 v0, 0xbfb8aa3b, v36
	v_exp_f32_e32 v0, v0
	global_store_dwordx2 v[66:67], v[34:35], off
	v_mul_f32_e32 v34, 0xbfb8aa3b, v37
	v_exp_f32_e32 v35, v34
	v_add_f32_e32 v0, 1.0, v0
	v_pk_mul_f32 v[54:55], v[56:57], v[140:141] op_sel_hi:[1,0]
	v_rcp_f32_e32 v34, v0
	v_add_f32_e32 v0, 1.0, v35
	v_mul_f32_e32 v35, 0xbfb8aa3b, v54
	v_exp_f32_e32 v56, v35
	v_mul_f32_e32 v35, 0xbfb8aa3b, v55
	v_exp_f32_e32 v57, v35
	v_rcp_f32_e32 v35, v0
	v_add_f32_e32 v0, 1.0, v56
	v_rcp_f32_e32 v56, v0
	v_add_f32_e32 v0, 1.0, v57
	v_rcp_f32_e32 v57, v0
	v_pk_mul_f32 v[38:39], v[38:39], v[140:141] op_sel_hi:[1,0]
	v_pk_mul_f32 v[34:35], v[36:37], v[34:35]
	v_pk_mul_f32 v[36:37], v[40:41], v[140:141] op_sel_hi:[1,0]
	v_pk_mul_f32 v[34:35], v[38:39], v[34:35]
	v_pk_mul_f32 v[38:39], v[54:55], v[56:57]
	v_lshl_add_u64 v[40:41], v[52:53], 0, s[20:21]
	v_pk_mul_f32 v[36:37], v[36:37], v[38:39]
	v_lshl_add_u64 v[38:39], v[50:51], 0, 16
	v_cvt_pk_bf16_f32 v34, v34, v35
	v_cvt_pk_bf16_f32 v35, v36, v37
	v_pk_mul_f32 v[36:37], v[58:59], v[140:141] op_sel_hi:[1,0]
	v_cndmask_b32_e64 v39, v41, v39, s[42:43]
	v_cndmask_b32_e64 v38, v40, v38, s[42:43]
	v_mul_f32_e32 v0, 0xbfb8aa3b, v36
	v_exp_f32_e32 v0, v0
	global_store_dwordx2 v[38:39], v[34:35], off
	v_mul_f32_e32 v34, 0xbfb8aa3b, v37
	v_exp_f32_e32 v35, v34
	v_add_f32_e32 v0, 1.0, v0
	v_pk_mul_f32 v[40:41], v[60:61], v[140:141] op_sel_hi:[1,0]
	v_rcp_f32_e32 v34, v0
	v_add_f32_e32 v0, 1.0, v35
	v_mul_f32_e32 v35, 0xbfb8aa3b, v40
	v_pk_mul_f32 v[38:39], v[42:43], v[140:141] op_sel_hi:[1,0]
	v_exp_f32_e32 v42, v35
	v_mul_f32_e32 v35, 0xbfb8aa3b, v41
	v_exp_f32_e32 v43, v35
	v_rcp_f32_e32 v35, v0
	v_add_f32_e32 v0, 1.0, v42
	v_rcp_f32_e32 v42, v0
	v_add_f32_e32 v0, 1.0, v43
	v_rcp_f32_e32 v43, v0
	v_pk_mul_f32 v[34:35], v[36:37], v[34:35]
	v_pk_mul_f32 v[36:37], v[44:45], v[140:141] op_sel_hi:[1,0]
	v_pk_mul_f32 v[34:35], v[38:39], v[34:35]
	v_pk_mul_f32 v[38:39], v[40:41], v[42:43]
	v_lshl_add_u64 v[40:41], v[52:53], 0, s[36:37]
	v_pk_mul_f32 v[36:37], v[36:37], v[38:39]
	v_lshl_add_u64 v[38:39], v[50:51], 0, 32
	v_cvt_pk_bf16_f32 v34, v34, v35
	v_cvt_pk_bf16_f32 v35, v36, v37
	v_pk_mul_f32 v[36:37], v[62:63], v[140:141] op_sel_hi:[1,0]
	v_cndmask_b32_e64 v39, v41, v39, s[40:41]
	v_cndmask_b32_e64 v38, v40, v38, s[40:41]
	v_mul_f32_e32 v0, 0xbfb8aa3b, v36
	v_exp_f32_e32 v0, v0
	global_store_dwordx2 v[38:39], v[34:35], off
	v_mul_f32_e32 v34, 0xbfb8aa3b, v37
	v_exp_f32_e32 v35, v34
	v_add_f32_e32 v0, 1.0, v0
	v_pk_mul_f32 v[40:41], v[64:65], v[140:141] op_sel_hi:[1,0]
	v_rcp_f32_e32 v34, v0
	v_add_f32_e32 v0, 1.0, v35
	v_mul_f32_e32 v35, 0xbfb8aa3b, v40
	v_exp_f32_e32 v42, v35
	v_mul_f32_e32 v35, 0xbfb8aa3b, v41
	v_exp_f32_e32 v43, v35
	v_rcp_f32_e32 v35, v0
	v_add_f32_e32 v0, 1.0, v42
	v_rcp_f32_e32 v42, v0
	v_add_f32_e32 v0, 1.0, v43
	v_rcp_f32_e32 v43, v0
	v_pk_mul_f32 v[38:39], v[46:47], v[140:141] op_sel_hi:[1,0]
	v_pk_mul_f32 v[34:35], v[36:37], v[34:35]
	v_pk_mul_f32 v[36:37], v[48:49], v[140:141] op_sel_hi:[1,0]
	v_pk_mul_f32 v[34:35], v[38:39], v[34:35]
	v_pk_mul_f32 v[38:39], v[40:41], v[42:43]
	v_lshl_add_u64 v[40:41], v[52:53], 0, s[4:5]
	v_pk_mul_f32 v[36:37], v[36:37], v[38:39]
	v_lshl_add_u64 v[38:39], v[50:51], 0, 48
	s_waitcnt lgkmcnt(0)
; DI void store4(u16* dst, float a, float b, float c, float d) { *(uint2*)dst = make_uint2(pack2(a, b), pack2(c, d)); }
; DI float sigmoidf_(float x) { return __builtin_amdgcn_rcpf(1.f + __expf(-x)); }
;     ...
; #pragma unroll
;   for (int i = 0; i < MI; ++i) {
;     const int m = m0 + wm * (MI * 32) + i * 32 + l32;
;     if (EPI == EPI_UP) {
;       const float rs = rsl[m - m0];
;       const int hb0 = nw >> 1;
; #pragma unroll
;       for (int gq = 0; gq < 4; ++gq) {
;         float v[4];
; #pragma unroll
;         for (int r = 0; r < 4; ++r) {
;           float gt = acc[i][0][4 * gq + r] * rs, up = acc[i][1][4 * gq + r] * rs;
;           v[r] = gt * sigmoidf_(gt) * up;
;         }
;         int hid = hb0 + 8 * gq + 4 * hh;
;         u16* dst = hid < 1408 ? p.regB + (size_t)m * 1408 + hid : (u16*)p.out + (size_t)m * 1408 + (hid - 1408);
;         store4(dst, v[0], v[1], v[2], v[3]);
;       }
	v_pk_mul_f32 v[18:19], v[18:19], v[138:139] op_sel_hi:[1,0]
	v_cndmask_b32_e32 v39, v41, v39, vcc
	v_cndmask_b32_e32 v38, v40, v38, vcc
	v_cvt_pk_bf16_f32 v34, v34, v35
	v_cvt_pk_bf16_f32 v35, v36, v37
	v_mul_f32_e32 v0, 0xbfb8aa3b, v18
	global_store_dwordx2 v[38:39], v[34:35], off
	v_exp_f32_e32 v0, v0
	v_mul_f32_e32 v38, 0xbfb8aa3b, v19
	v_exp_f32_e32 v39, v38
	v_pk_mul_f32 v[20:21], v[20:21], v[138:139] op_sel_hi:[1,0]
	v_add_f32_e32 v0, 1.0, v0
	v_rcp_f32_e32 v38, v0
	v_add_f32_e32 v0, 1.0, v39
	v_mul_f32_e32 v39, 0xbfb8aa3b, v20
	v_exp_f32_e32 v40, v39
	v_mul_f32_e32 v39, 0xbfb8aa3b, v21
	v_exp_f32_e32 v41, v39
	v_rcp_f32_e32 v39, v0
	v_add_f32_e32 v0, 1.0, v40
	v_rcp_f32_e32 v40, v0
	v_add_f32_e32 v0, 1.0, v41
	v_rcp_f32_e32 v41, v0
	v_pk_mul_f32 v[2:3], v[2:3], v[138:139] op_sel_hi:[1,0]
	v_pk_mul_f32 v[18:19], v[18:19], v[38:39]
	v_mad_i64_i32 v[34:35], s[16:17], v143, s29, v[130:131]
	v_pk_mul_f32 v[2:3], v[2:3], v[18:19]
	v_pk_mul_f32 v[4:5], v[4:5], v[138:139] op_sel_hi:[1,0]
	v_pk_mul_f32 v[18:19], v[20:21], v[40:41]
	v_mad_i64_i32 v[36:37], s[16:17], v143, s29, v[132:133]
	v_pk_mul_f32 v[4:5], v[4:5], v[18:19]
	v_lshl_add_u64 v[20:21], v[34:35], 0, v[100:101]
	v_lshl_add_u64 v[18:19], v[36:37], 0, v[98:99]
	v_lshl_add_u64 v[34:35], v[20:21], 0, s[18:19]
	v_cvt_pk_bf16_f32 v2, v2, v3
	v_cvt_pk_bf16_f32 v3, v4, v5
	v_pk_mul_f32 v[4:5], v[22:23], v[138:139] op_sel_hi:[1,0]
	v_cndmask_b32_e64 v35, v35, v19, s[44:45]
	v_cndmask_b32_e64 v34, v34, v18, s[44:45]
	v_mul_f32_e32 v0, 0xbfb8aa3b, v4
	v_exp_f32_e32 v0, v0
	global_store_dwordx2 v[34:35], v[2:3], off
	v_mul_f32_e32 v2, 0xbfb8aa3b, v5
	v_exp_f32_e32 v3, v2
	v_add_f32_e32 v0, 1.0, v0
	v_pk_mul_f32 v[22:23], v[24:25], v[138:139] op_sel_hi:[1,0]
	v_rcp_f32_e32 v2, v0
	v_add_f32_e32 v0, 1.0, v3
	v_mul_f32_e32 v3, 0xbfb8aa3b, v22
	v_exp_f32_e32 v24, v3
	v_mul_f32_e32 v3, 0xbfb8aa3b, v23
	v_exp_f32_e32 v25, v3
	v_rcp_f32_e32 v3, v0
	v_add_f32_e32 v0, 1.0, v24
	v_rcp_f32_e32 v24, v0
	v_add_f32_e32 v0, 1.0, v25
	v_rcp_f32_e32 v25, v0
	v_pk_mul_f32 v[6:7], v[6:7], v[138:139] op_sel_hi:[1,0]
	v_pk_mul_f32 v[2:3], v[4:5], v[2:3]
	v_pk_mul_f32 v[4:5], v[8:9], v[138:139] op_sel_hi:[1,0]
	v_pk_mul_f32 v[2:3], v[6:7], v[2:3]
	v_pk_mul_f32 v[6:7], v[22:23], v[24:25]
	v_lshl_add_u64 v[8:9], v[20:21], 0, s[20:21]
	v_pk_mul_f32 v[4:5], v[4:5], v[6:7]
	v_lshl_add_u64 v[6:7], v[18:19], 0, 16
	v_cvt_pk_bf16_f32 v2, v2, v3
	v_cvt_pk_bf16_f32 v3, v4, v5
	v_pk_mul_f32 v[4:5], v[26:27], v[138:139] op_sel_hi:[1,0]
	v_cndmask_b32_e64 v7, v9, v7, s[42:43]
	v_cndmask_b32_e64 v6, v8, v6, s[42:43]
	v_mul_f32_e32 v0, 0xbfb8aa3b, v4
	v_exp_f32_e32 v0, v0
	global_store_dwordx2 v[6:7], v[2:3], off
	v_mul_f32_e32 v2, 0xbfb8aa3b, v5
	v_exp_f32_e32 v3, v2
	v_add_f32_e32 v0, 1.0, v0
	v_pk_mul_f32 v[8:9], v[28:29], v[138:139] op_sel_hi:[1,0]
	v_rcp_f32_e32 v2, v0
	v_add_f32_e32 v0, 1.0, v3
	v_mul_f32_e32 v3, 0xbfb8aa3b, v8
	v_pk_mul_f32 v[6:7], v[10:11], v[138:139] op_sel_hi:[1,0]
	v_exp_f32_e32 v10, v3
	v_mul_f32_e32 v3, 0xbfb8aa3b, v9
	v_exp_f32_e32 v11, v3
	v_rcp_f32_e32 v3, v0
	v_add_f32_e32 v0, 1.0, v10
	v_rcp_f32_e32 v10, v0
	v_add_f32_e32 v0, 1.0, v11
	v_rcp_f32_e32 v11, v0
	v_pk_mul_f32 v[2:3], v[4:5], v[2:3]
	v_pk_mul_f32 v[4:5], v[12:13], v[138:139] op_sel_hi:[1,0]
	v_pk_mul_f32 v[2:3], v[6:7], v[2:3]
	v_pk_mul_f32 v[6:7], v[8:9], v[10:11]
	v_lshl_add_u64 v[8:9], v[20:21], 0, s[36:37]
	v_pk_mul_f32 v[4:5], v[4:5], v[6:7]
	v_lshl_add_u64 v[6:7], v[18:19], 0, 32
	v_cvt_pk_bf16_f32 v2, v2, v3
	v_cvt_pk_bf16_f32 v3, v4, v5
	v_pk_mul_f32 v[4:5], v[30:31], v[138:139] op_sel_hi:[1,0]
	v_cndmask_b32_e64 v7, v9, v7, s[40:41]
	v_cndmask_b32_e64 v6, v8, v6, s[40:41]
	v_mul_f32_e32 v0, 0xbfb8aa3b, v4
	v_exp_f32_e32 v0, v0
	global_store_dwordx2 v[6:7], v[2:3], off
	v_mul_f32_e32 v2, 0xbfb8aa3b, v5
	v_exp_f32_e32 v3, v2
	v_add_f32_e32 v0, 1.0, v0
	v_pk_mul_f32 v[8:9], v[32:33], v[138:139] op_sel_hi:[1,0]
	v_rcp_f32_e32 v2, v0
	v_add_f32_e32 v0, 1.0, v3
	v_mul_f32_e32 v3, 0xbfb8aa3b, v8
	v_exp_f32_e32 v10, v3
	v_mul_f32_e32 v3, 0xbfb8aa3b, v9
	v_exp_f32_e32 v11, v3
	v_rcp_f32_e32 v3, v0
	v_add_f32_e32 v0, 1.0, v10
	v_rcp_f32_e32 v10, v0
	v_add_f32_e32 v0, 1.0, v11
	v_rcp_f32_e32 v11, v0
	v_pk_mul_f32 v[6:7], v[14:15], v[138:139] op_sel_hi:[1,0]
	v_pk_mul_f32 v[2:3], v[4:5], v[2:3]
	v_pk_mul_f32 v[4:5], v[16:17], v[138:139] op_sel_hi:[1,0]
	v_pk_mul_f32 v[2:3], v[6:7], v[2:3]
	v_pk_mul_f32 v[6:7], v[8:9], v[10:11]
	v_lshl_add_u64 v[8:9], v[20:21], 0, s[4:5]
	v_pk_mul_f32 v[4:5], v[4:5], v[6:7]
	v_lshl_add_u64 v[6:7], v[18:19], 0, 48
	v_cndmask_b32_e32 v7, v9, v7, vcc
	v_cndmask_b32_e32 v6, v8, v6, vcc
	v_cvt_pk_bf16_f32 v2, v2, v3
	v_cvt_pk_bf16_f32 v3, v4, v5
	s_mov_b64 s[16:17], 0
	s_and_b64 vcc, exec, s[10:11]
	global_store_dwordx2 v[6:7], v[2:3], off
	s_cbranch_vccnz .LBB0_1376
; DI float rstd16(const float* ssq, int m) {
;   float s = 0.f;
; #pragma unroll
;   for (int c = 0; c < 16; ++c) s += ssq[(size_t)c * TP + m];
;   return rsqrtf(s * (1.f / 1024.f) + RMS_EPS);
; }
;     ...
;   if ((EPI == EPI_UP || EPI == EPI_INPROJ) && tid < 256) rs_early = rstd16(p.ssq, m0 + tid);
.LBB0_1364:
	s_cmpk_gt_u32 s51, 0xaf
	s_cselect_b64 s[10:11], -1, 0
	s_and_b64 s[40:41], s[10:11], exec
	s_cselect_b32 s40, 64, 0
	s_lshl_b32 s41, s51, 3
	s_and_b32 s41, s41, 56
	s_or_b32 s40, s41, s40
	s_or_b32 s40, s40, s72
	v_mov_b32_e32 v154, v179
	s_lshl_b32 s44, s40, 8
	v_cmp_gt_i32_e64 s[40:41], s73, v154
	v_mov_b32_e32 v155, 0
	s_and_saveexec_b64 s[42:43], s[40:41]
	s_cbranch_execz .LBB0_1366
	s_load_dwordx2 s[52:53], s[0:1], 0x128
	v_add_u32_e32 v2, s44, v154
	v_ashrrev_i32_e32 v3, 31, v2
	s_mov_b32 s45, 0x800000
	s_waitcnt lgkmcnt(0)
	v_lshl_add_u64 v[2:3], v[2:3], 2, s[52:53]
	s_waitcnt vmcnt(16)
	v_add_f32_e32 v0, 0, v204
	v_add_f32_e32 v0, v0, v205
	v_add_f32_e32 v0, v0, v206
	v_add_f32_e32 v0, v0, v207
	v_add_f32_e32 v0, v0, v208
	v_add_f32_e32 v0, v0, v209
	v_add_f32_e32 v0, v0, v210
	v_add_f32_e32 v0, v0, v211
	v_add_f32_e32 v0, v0, v212
	v_add_f32_e32 v0, v0, v213
	v_add_f32_e32 v0, v0, v214
	v_add_f32_e32 v0, v0, v215
	v_add_f32_e32 v0, v0, v216
	v_add_f32_e32 v0, v0, v217
	v_add_f32_e32 v0, v0, v218
	v_add_f32_e32 v0, v0, v219
	v_fmamk_f32 v0, v0, 0x3a800000, v180
	v_mul_f32_e32 v2, 0x4b800000, v0
	v_cmp_gt_f32_e32 vcc, s45, v0
	s_nop 1
	v_cndmask_b32_e32 v0, v0, v2, vcc
	v_rsq_f32_e32 v0, v0
	s_nop 0
	v_mul_f32_e32 v2, 0x45800000, v0
	v_cndmask_b32_e32 v155, v0, v2, vcc
.LBB0_1366:
	s_or_b64 exec, exec, s[42:43]
	s_xor_b64 s[16:17], s[16:17], -1
	s_and_b64 s[10:11], s[10:11], exec
	v_ashrrev_i32_e32 v27, 6, v154
	s_cselect_b32 s10, 0xffffff50, 0
	v_bfe_u32 v24, v154, 3, 3
	v_lshlrev_b32_e32 v25, 5, v27
	v_bfe_u32 v0, v154, 4, 2
	s_add_i32 s10, s10, s51
	v_or_b32_e32 v156, v24, v25
	v_bitop3_b32 v0, v0, v154, 63 bitop3:0x78
	v_and_b32_e32 v26, 63, v154
	s_lshl_b32 s10, s10, 5
	v_lshlrev_b32_e32 v0, 3, v0
	v_lshlrev_b32_e32 v2, 2, v27
	v_add_u32_e32 v18, s44, v156
	s_and_b32 s42, s10, 0xffffff00
	s_mov_b64 s[10:11], -1
	s_andn2_b64 vcc, exec, s[16:17]
	v_and_b32_e32 v0, 56, v0
	v_lshlrev_b32_e32 v28, 4, v26
	v_or_b32_e32 v31, 1, v2
	v_or_b32_e32 v30, 2, v2
	v_or_b32_e32 v29, 3, v2
	v_ashrrev_i32_e32 v19, 31, v18
	s_cbranch_vccnz .LBB0_1368
	v_lshl_or_b32 v164, v30, 3, v24
	v_lshrrev_b32_e32 v4, 1, v164
	v_xor_b32_e32 v4, v4, v154
	v_lshl_or_b32 v158, v31, 3, v24
	v_lshlrev_b32_e32 v4, 3, v4
	v_lshl_or_b32 v166, v29, 3, v24
	v_lshrrev_b32_e32 v2, 1, v158
	v_and_b32_e32 v6, 56, v4
	v_lshrrev_b32_e32 v4, 1, v166
	v_xor_b32_e32 v2, v2, v154
	v_xor_b32_e32 v4, v4, v154
	v_add_u32_e32 v8, s44, v158
	v_add_u32_e32 v10, s44, v164
	v_add_u32_e32 v14, s44, v166
	v_add_u32_e32 v16, s42, v158
	v_add_u32_e32 v20, s42, v164
	v_add_u32_e32 v22, s42, v166
	v_lshlrev_b32_e32 v2, 3, v2
	v_lshlrev_b32_e32 v4, 3, v4
	v_ashrrev_i32_e32 v9, 31, v8
	v_ashrrev_i32_e32 v11, 31, v10
	v_ashrrev_i32_e32 v15, 31, v14
	v_ashrrev_i32_e32 v17, 31, v16
	v_ashrrev_i32_e32 v21, 31, v20
	v_ashrrev_i32_e32 v23, 31, v22
	v_lshlrev_b32_e32 v168, 4, v26
	v_and_b32_e32 v2, 56, v2
	v_mov_b32_e32 v3, v1
	v_lshlrev_b32_e32 v157, 10, v31
	v_mov_b32_e32 v7, v1
	v_lshlrev_b32_e32 v159, 10, v30
	v_and_b32_e32 v12, 56, v4
	v_mov_b32_e32 v13, v1
	v_lshlrev_b32_e32 v165, 10, v29
	v_lshlrev_b64 v[4:5], 11, v[18:19]
	v_lshlrev_b64 v[8:9], 11, v[8:9]
	v_lshlrev_b64 v[10:11], 11, v[10:11]
	v_lshlrev_b64 v[14:15], 11, v[14:15]
	v_lshlrev_b64 v[16:17], 11, v[16:17]
	v_lshlrev_b64 v[20:21], 11, v[20:21]
	v_lshlrev_b64 v[22:23], 11, v[22:23]
	s_mov_b64 s[10:11], 0

; #define MFMA(a, b, c) __builtin_amdgcn_mfma_f32_32x32x16_bf16((a), (b), (c), 0, 0, 0)
;     ...
;     auto issue_at = [&](int mm0, int nn0, int kt, int buf) {
;       char* lb = L0 + buf * BUFB;
; #pragma unroll
;       for (int i = 0; i < 4; ++i) {
;         const int seg = wv * 4 + i, row = seg * 8 + gl_row;
;         const int c = (lane & 7) ^ ((row >> 1) & 7);
;         const u16* ap = (kt < g.split) ? g.a0 + (size_t)(mm0 + row) * g.ld0 + kt * g.ks0 : g.a1 + (size_t)(mm0 + row) * g.ld1 + (kt - g.split) * 64;
;         __builtin_amdgcn_global_load_lds((const unsigned*)(ap + c * 8), (__attribute__((address_space(3))) unsigned*)(lb + seg * 1024 + lane * 16), 16, 0, 0);
;       }
; #pragma unroll
;       for (int i = 0; i < BN / 64; ++i) {
;         const int seg = wv * (BN / 64) + i, row = seg * 8 + gl_row;
;         const int c = (lane & 7) ^ ((row >> 1) & 7);
;         __builtin_amdgcn_global_load_lds((const unsigned*)(g.W + (size_t)(nn0 + row) * g.K + kt * 64 + c * 8),
;                                          (__attribute__((address_space(3))) unsigned*)(lb + 256 * 128 + seg * 1024 + lane * 16), 16, 0, 0);
;       }
;     };
;     auto issue = [&](int kt, int buf) { issue_at(m0, n0, kt, buf); };
;     auto compute2 = [&](int buf) {
;       const char* lb = L0 + buf * BUFB;
; #pragma unroll
;       for (int ks = 0; ks < 4; ++ks) {
;         const int c = ks * 2 + hh;
;         bf16x8 wf[2], xf[MI];
; #pragma unroll
;         for (int j = 0; j < 2; ++j) { const int r = wn * 64 + j * 32 + l32; wf[j] = *(const bf16x8*)(lb + 256 * 128 + r * 128 + ((c ^ ((r >> 1) & 7)) << 4)); }
; #pragma unroll
;         for (int i = 0; i < MI; ++i) { const int r = wm * (MI * 32) + i * 32 + l32; xf[i] = *(const bf16x8*)(lb + r * 128 + ((c ^ ((r >> 1) & 7)) << 4)); }
; #pragma unroll
;         for (int i = 0; i < MI; ++i) {
;           acc[i][0] = MFMA(wf[0], xf[i], acc[i][0]);
;           acc[i][1] = MFMA(wf[1], xf[i], acc[i][1]);
;         }
;       }
;     };
;     ...
;       if (!(chain & 1)) {
;         issue(0, 0);
;         asm volatile("s_waitcnt vmcnt(0)" ::: "memory");
;         __syncthreads();
;       }
;       for (int kt = 0; kt < nk; ++kt) {
;         const int buf = kt & 1;
;         if (kt + 1 < nk) issue(kt + 1, buf ^ 1);
;         else if (chain & 2) issue_at(nmt * 256, nnt * BN, 0, buf ^ 1);
;         compute2(buf);
.LBB0_1370:
	v_lshlrev_b64 v[136:137], 1, v[2:3]
	v_lshl_add_u64 v[2:3], v[16:17], 0, v[136:137]
	v_lshrrev_b32_e32 v18, 30, v27
	v_lshl_add_u64 v[142:143], s[2:3], 0, v[2:3]
	v_or_b32_e32 v2, s42, v24
	v_add_u32_e32 v18, v27, v18
	v_add_u32_e32 v2, v2, v25
	v_ashrrev_i32_e32 v160, 2, v18
	v_ashrrev_i32_e32 v3, 31, v2
	v_mul_i32_i24_e32 v18, 4, v160
	v_lshlrev_b64 v[2:3], 11, v[2:3]
	v_lshlrev_b64 v[134:135], 1, v[0:1]
	v_sub_u32_e32 v163, v27, v18
	v_lshrrev_b32_e32 v161, 5, v26
	v_lshrrev_b32_e32 v18, 1, v154
	v_lshlrev_b64 v[130:131], 1, v[12:13]
	v_lshl_add_u64 v[2:3], v[2:3], 0, v[134:135]
	v_and_b32_e32 v162, 31, v154
	v_bitop3_b32 v18, v18, v161, 7 bitop3:0x6c
	v_lshlrev_b64 v[132:133], 1, v[6:7]
	v_lshl_add_u64 v[144:145], s[2:3], 0, v[2:3]
	v_lshl_add_u64 v[2:3], v[14:15], 0, v[130:131]
	v_bfe_u32 v19, v154, 1, 3
	v_lshlrev_b32_e32 v174, 4, v18
	v_lshlrev_b32_e32 v18, 7, v162
	v_lshl_add_u64 v[146:147], s[14:15], 0, v[2:3]
	v_lshl_add_u64 v[2:3], v[10:11], 0, v[132:133]
	v_lshl_or_b32 v170, v163, 13, v18
	v_lshl_or_b32 v169, v160, 14, v18
	v_bitop3_b32 v18, v161, v19, 2 bitop3:0x36
	v_lshl_add_u64 v[148:149], s[14:15], 0, v[2:3]
	v_lshl_add_u64 v[2:3], v[8:9], 0, v[136:137]
	v_lshlrev_b32_e32 v173, 4, v18
	v_bitop3_b32 v18, v161, v19, 4 bitop3:0x36
	v_lshl_add_u64 v[150:151], s[14:15], 0, v[2:3]
	v_lshl_add_u64 v[2:3], v[4:5], 0, v[134:135]
	v_lshlrev_b32_e32 v172, 4, v18
	v_bitop3_b32 v18, v161, v19, 6 bitop3:0x36
	v_lshl_add_u64 v[12:13], v[22:23], 0, v[130:131]
	v_lshl_add_u64 v[6:7], v[20:21], 0, v[132:133]
	v_lshl_add_u64 v[152:153], s[14:15], 0, v[2:3]
	v_mov_b32_e32 v2, 0
	v_lshlrev_b32_e32 v171, 4, v18
	v_lshl_add_u64 v[138:139], s[2:3], 0, v[12:13]
	v_lshl_add_u64 v[140:141], s[2:3], 0, v[6:7]
	s_mov_b32 s16, 0
	s_mov_b64 s[10:11], 0
	v_mov_b32_e32 v3, v2
	v_mov_b32_e32 v4, v2
	v_mov_b32_e32 v5, v2
	v_mov_b32_e32 v6, v2
	v_mov_b32_e32 v7, v2
	v_mov_b32_e32 v8, v2
	v_mov_b32_e32 v9, v2
	v_mov_b32_e32 v10, v2
	v_mov_b32_e32 v11, v2
	v_mov_b32_e32 v12, v2
	v_mov_b32_e32 v13, v2
	v_mov_b32_e32 v14, v2
	v_mov_b32_e32 v15, v2
	v_mov_b32_e32 v16, v2
	v_mov_b32_e32 v17, v2
	v_mov_b32_e32 v18, v2
	v_mov_b32_e32 v19, v2
	v_mov_b32_e32 v20, v2
	v_mov_b32_e32 v21, v2
	v_mov_b32_e32 v22, v2
	v_mov_b32_e32 v23, v2
	v_mov_b32_e32 v24, v2
	v_mov_b32_e32 v25, v2
	v_mov_b32_e32 v26, v2
	v_mov_b32_e32 v27, v2
	v_mov_b32_e32 v28, v2
	v_mov_b32_e32 v29, v2
	v_mov_b32_e32 v30, v2
	v_mov_b32_e32 v31, v2
	v_mov_b32_e32 v32, v2
	v_mov_b32_e32 v33, v2
	v_mov_b32_e32 v34, v2
	v_mov_b32_e32 v35, v2
	v_mov_b32_e32 v36, v2
	v_mov_b32_e32 v37, v2
	v_mov_b32_e32 v38, v2
	v_mov_b32_e32 v39, v2
	v_mov_b32_e32 v40, v2
	v_mov_b32_e32 v41, v2
	v_mov_b32_e32 v42, v2
	v_mov_b32_e32 v43, v2
	v_mov_b32_e32 v44, v2
	v_mov_b32_e32 v45, v2
	v_mov_b32_e32 v46, v2
	v_mov_b32_e32 v47, v2
	v_mov_b32_e32 v48, v2
	v_mov_b32_e32 v49, v2
	v_mov_b32_e32 v50, v2
	v_mov_b32_e32 v51, v2
	v_mov_b32_e32 v52, v2
	v_mov_b32_e32 v53, v2
	v_mov_b32_e32 v54, v2
	v_mov_b32_e32 v55, v2
	v_mov_b32_e32 v56, v2
	v_mov_b32_e32 v57, v2
	v_mov_b32_e32 v58, v2
	v_mov_b32_e32 v59, v2
	v_mov_b32_e32 v60, v2
	v_mov_b32_e32 v61, v2
	v_mov_b32_e32 v62, v2
	v_mov_b32_e32 v63, v2
	v_mov_b32_e32 v64, v2
	v_mov_b32_e32 v65, v2
	v_mov_b32_e32 v66, v2
	v_mov_b32_e32 v67, v2
	v_mov_b32_e32 v68, v2
	v_mov_b32_e32 v69, v2
	v_mov_b32_e32 v70, v2
	v_mov_b32_e32 v71, v2
	v_mov_b32_e32 v72, v2
	v_mov_b32_e32 v73, v2
	v_mov_b32_e32 v74, v2
	v_mov_b32_e32 v75, v2
	v_mov_b32_e32 v76, v2
	v_mov_b32_e32 v77, v2
	v_mov_b32_e32 v78, v2
	v_mov_b32_e32 v79, v2
	v_mov_b32_e32 v80, v2
	v_mov_b32_e32 v81, v2
	v_mov_b32_e32 v82, v2
	v_mov_b32_e32 v83, v2
	v_mov_b32_e32 v84, v2
	v_mov_b32_e32 v85, v2
	v_mov_b32_e32 v86, v2
	v_mov_b32_e32 v87, v2
	v_mov_b32_e32 v88, v2
	v_mov_b32_e32 v89, v2
	v_mov_b32_e32 v90, v2
	v_mov_b32_e32 v91, v2
	v_mov_b32_e32 v92, v2
	v_mov_b32_e32 v93, v2
	v_mov_b32_e32 v94, v2
	v_mov_b32_e32 v95, v2
	v_mov_b32_e32 v96, v2
	v_mov_b32_e32 v97, v2
	v_mov_b32_e32 v98, v2
	v_mov_b32_e32 v99, v2
	v_mov_b32_e32 v100, v2
	v_mov_b32_e32 v101, v2
	v_mov_b32_e32 v102, v2
	v_mov_b32_e32 v103, v2
	v_mov_b32_e32 v104, v2
	v_mov_b32_e32 v105, v2
	v_mov_b32_e32 v106, v2
	v_mov_b32_e32 v107, v2
	v_mov_b32_e32 v108, v2
	v_mov_b32_e32 v109, v2
	v_mov_b32_e32 v110, v2
	v_mov_b32_e32 v111, v2
	v_mov_b32_e32 v112, v2
	v_mov_b32_e32 v113, v2
	v_mov_b32_e32 v114, v2
	v_mov_b32_e32 v115, v2
	v_mov_b32_e32 v116, v2
	v_mov_b32_e32 v117, v2
	v_mov_b32_e32 v118, v2
	v_mov_b32_e32 v119, v2
	v_mov_b32_e32 v120, v2
	v_mov_b32_e32 v121, v2
	v_mov_b32_e32 v122, v2
	v_mov_b32_e32 v123, v2
	v_mov_b32_e32 v124, v2
	v_mov_b32_e32 v125, v2
	v_mov_b32_e32 v126, v2
	v_mov_b32_e32 v127, v2
	v_mov_b32_e32 v128, v2
	v_mov_b32_e32 v129, v2
.LBB0_1371:
	s_waitcnt vmcnt(16)
	s_barrier
	s_and_b32 s17, s16, 0x10000
	s_xor_b32 s43, s17, 0x10000
	s_add_i32 s43, s43, 0
	s_add_i32 s17, s17, 0
	v_add_u32_e32 v0, s17, v174
	v_add_u32_e32 v175, v0, v170
	v_add_u32_e32 v0, v0, v169
	ds_read_b128 v[200:203], v175 offset:32768
	ds_read_b128 v[204:207], v175 offset:36864
	ds_read_b128 v[208:211], v0
	ds_read_b128 v[212:215], v0 offset:4096
	ds_read_b128 v[216:219], v0 offset:8192
	ds_read_b128 v[220:223], v0 offset:12288
	v_add3_u32 v0, s43, v167, v168
	v_add3_u32 v175, s43, v157, v168
	v_readfirstlane_b32 s45, v0
	v_lshl_add_u64 v[176:177], v[152:153], 0, s[10:11]
	s_mov_b32 m0, s45
	v_readfirstlane_b32 s45, v175
	v_add3_u32 v178, s43, v159, v168
	global_load_lds_dwordx4 v[176:177], off
	v_lshl_add_u64 v[176:177], v[150:151], 0, s[10:11]
	s_mov_b32 m0, s45
	v_readfirstlane_b32 s45, v178
	v_add3_u32 v199, s43, v165, v168
	global_load_lds_dwordx4 v[176:177], off
	v_lshl_add_u64 v[176:177], v[148:149], 0, s[10:11]
	s_mov_b32 m0, s45
	v_readfirstlane_b32 s43, v199
	v_add_u32_e32 v0, 0x8000, v0
	global_load_lds_dwordx4 v[176:177], off
	v_lshl_add_u64 v[176:177], v[146:147], 0, s[10:11]
	s_mov_b32 m0, s43
	v_readfirstlane_b32 s43, v0
	v_add_u32_e32 v0, 0x8000, v175
	global_load_lds_dwordx4 v[176:177], off
	v_lshl_add_u64 v[176:177], v[144:145], 0, s[10:11]
	s_mov_b32 m0, s43
	v_readfirstlane_b32 s43, v0
	v_add_u32_e32 v0, 0x8000, v178
	global_load_lds_dwordx4 v[176:177], off
	v_lshl_add_u64 v[176:177], v[142:143], 0, s[10:11]
	s_mov_b32 m0, s43
	v_readfirstlane_b32 s43, v0
	v_add_u32_e32 v0, 0x8000, v199
	global_load_lds_dwordx4 v[176:177], off
	v_lshl_add_u64 v[176:177], v[140:141], 0, s[10:11]
	s_mov_b32 m0, s43
	v_readfirstlane_b32 s43, v0
	global_load_lds_dwordx4 v[176:177], off
	v_lshl_add_u64 v[176:177], v[138:139], 0, s[10:11]
	s_mov_b32 m0, s43
	global_load_lds_dwordx4 v[176:177], off

; #define MFMA(a, b, c) __builtin_amdgcn_mfma_f32_32x32x16_bf16((a), (b), (c), 0, 0, 0)
;     ...
;     auto compute2 = [&](int buf) {
;       const char* lb = L0 + buf * BUFB;
; #pragma unroll
;       for (int ks = 0; ks < 4; ++ks) {
;         const int c = ks * 2 + hh;
;         bf16x8 wf[2], xf[MI];
; #pragma unroll
;         for (int j = 0; j < 2; ++j) { const int r = wn * 64 + j * 32 + l32; wf[j] = *(const bf16x8*)(lb + 256 * 128 + r * 128 + ((c ^ ((r >> 1) & 7)) << 4)); }
; #pragma unroll
;         for (int i = 0; i < MI; ++i) { const int r = wm * (MI * 32) + i * 32 + l32; xf[i] = *(const bf16x8*)(lb + r * 128 + ((c ^ ((r >> 1) & 7)) << 4)); }
; #pragma unroll
;         for (int i = 0; i < MI; ++i) {
;           acc[i][0] = MFMA(wf[0], xf[i], acc[i][0]);
;           acc[i][1] = MFMA(wf[1], xf[i], acc[i][1]);
;         }
;       }
;     };
;     ...
;   if (EPI == EPI_UP || EPI == EPI_INPROJ) {
;     if (tid < 256) rsl[tid] = rs_early;
;     __syncthreads();
.LBB0_1374:
	v_add3_u32 v0, s25, v174, v170
	v_add3_u32 v142, s24, v174, v169
	ds_read_b128 v[130:133], v0
	ds_read_b128 v[138:141], v0 offset:4096
	ds_read_b128 v[134:137], v142
	ds_read_b128 v[204:207], v142 offset:4096
	ds_read_b128 v[208:211], v142 offset:8192
	ds_read_b128 v[212:215], v142 offset:12288
	v_add3_u32 v0, s25, v173, v170
	v_add3_u32 v142, s24, v173, v169
	s_waitcnt lgkmcnt(3)
	v_mfma_f32_32x32x16_bf16 v[114:129], v[130:133], v[134:137], v[114:129]
	ds_read_b128 v[216:219], v0
	v_mfma_f32_32x32x16_bf16 v[98:113], v[138:141], v[134:137], v[98:113]
	ds_read_b128 v[220:223], v0 offset:4096
	s_waitcnt lgkmcnt(4)
	v_mfma_f32_32x32x16_bf16 v[82:97], v[130:133], v[204:207], v[82:97]
	ds_read_b128 v[224:227], v142
	v_mfma_f32_32x32x16_bf16 v[66:81], v[138:141], v[204:207], v[66:81]
	ds_read_b128 v[204:207], v142 offset:4096
	s_waitcnt lgkmcnt(5)
	v_mfma_f32_32x32x16_bf16 v[50:65], v[130:133], v[208:211], v[50:65]
	v_mfma_f32_32x32x16_bf16 v[34:49], v[138:141], v[208:211], v[34:49]
	ds_read_b128 v[208:211], v142 offset:8192
	s_waitcnt lgkmcnt(5)
	v_mfma_f32_32x32x16_bf16 v[18:33], v[130:133], v[212:215], v[18:33]
	v_mfma_f32_32x32x16_bf16 v[2:17], v[138:141], v[212:215], v[2:17]
	ds_read_b128 v[212:215], v142 offset:12288
	v_add3_u32 v0, s25, v172, v170
	v_add3_u32 v142, s24, v172, v169
	s_waitcnt lgkmcnt(3)
	v_mfma_f32_32x32x16_bf16 v[114:129], v[216:219], v[224:227], v[114:129]
	ds_read_b128 v[130:133], v0
	v_mfma_f32_32x32x16_bf16 v[98:113], v[220:223], v[224:227], v[98:113]
	ds_read_b128 v[138:141], v0 offset:4096
	s_waitcnt lgkmcnt(4)
	v_mfma_f32_32x32x16_bf16 v[82:97], v[216:219], v[204:207], v[82:97]
	ds_read_b128 v[134:137], v142
	v_mfma_f32_32x32x16_bf16 v[66:81], v[220:223], v[204:207], v[66:81]
	ds_read_b128 v[204:207], v142 offset:4096
	s_waitcnt lgkmcnt(5)
	v_mfma_f32_32x32x16_bf16 v[50:65], v[216:219], v[208:211], v[50:65]
	v_mfma_f32_32x32x16_bf16 v[34:49], v[220:223], v[208:211], v[34:49]
	ds_read_b128 v[208:211], v142 offset:8192
	s_waitcnt lgkmcnt(5)
	v_mfma_f32_32x32x16_bf16 v[18:33], v[216:219], v[212:215], v[18:33]
	v_mfma_f32_32x32x16_bf16 v[2:17], v[220:223], v[212:215], v[2:17]
	ds_read_b128 v[212:215], v142 offset:12288
	v_add3_u32 v0, s25, v171, v170
	v_add3_u32 v142, s24, v171, v169
	s_waitcnt lgkmcnt(3)
	v_mfma_f32_32x32x16_bf16 v[114:129], v[130:133], v[134:137], v[114:129]
	ds_read_b128 v[216:219], v0
	v_mfma_f32_32x32x16_bf16 v[98:113], v[138:141], v[134:137], v[98:113]
	ds_read_b128 v[220:223], v0 offset:4096
	s_waitcnt lgkmcnt(4)
	v_mfma_f32_32x32x16_bf16 v[82:97], v[130:133], v[204:207], v[82:97]
	ds_read_b128 v[224:227], v142
	v_mfma_f32_32x32x16_bf16 v[66:81], v[138:141], v[204:207], v[66:81]
	ds_read_b128 v[204:207], v142 offset:4096
	s_waitcnt lgkmcnt(5)
	v_mfma_f32_32x32x16_bf16 v[50:65], v[130:133], v[208:211], v[50:65]
	v_mfma_f32_32x32x16_bf16 v[34:49], v[138:141], v[208:211], v[34:49]
	ds_read_b128 v[208:211], v142 offset:8192
	s_waitcnt lgkmcnt(5)
	v_mfma_f32_32x32x16_bf16 v[18:33], v[130:133], v[212:215], v[18:33]
	v_mfma_f32_32x32x16_bf16 v[2:17], v[138:141], v[212:215], v[2:17]
	ds_read_b128 v[212:215], v142 offset:12288
	s_waitcnt lgkmcnt(0)
	s_barrier
	s_barrier
	v_mfma_f32_32x32x16_bf16 v[114:129], v[216:219], v[224:227], v[114:129]
	v_mfma_f32_32x32x16_bf16 v[98:113], v[220:223], v[224:227], v[98:113]
	v_mfma_f32_32x32x16_bf16 v[82:97], v[216:219], v[204:207], v[82:97]
	v_mfma_f32_32x32x16_bf16 v[66:81], v[220:223], v[204:207], v[66:81]
	v_mfma_f32_32x32x16_bf16 v[50:65], v[216:219], v[208:211], v[50:65]
	v_mfma_f32_32x32x16_bf16 v[34:49], v[220:223], v[208:211], v[34:49]
	v_mfma_f32_32x32x16_bf16 v[18:33], v[216:219], v[212:215], v[18:33]
	v_mfma_f32_32x32x16_bf16 v[2:17], v[220:223], v[212:215], v[2:17]
	s_and_saveexec_b64 s[16:17], s[40:41]
	s_cbranch_execz .LBB0_1363
	v_lshl_add_u32 v0, v154, 2, 0
	v_add_u32_e32 v0, 0x24000, v0
	ds_write_b32 v0, v155
	s_branch .LBB0_1363

; DI float rstd16(const float* ssq, int m) {
;   float s = 0.f;
; #pragma unroll
;   for (int c = 0; c < 16; ++c) s += ssq[(size_t)c * TP + m];
;   return rsqrtf(s * (1.f / 1024.f) + RMS_EPS);
; }
.LBB0_1379:
	v_mov_b32_e32 v34, v179
	v_mov_b32_e32 v35, 0
	v_cmp_gt_i32_e64 s[40:41], s73, v34
	s_and_saveexec_b64 s[2:3], s[40:41]
	s_cbranch_execz .LBB0_1381
	s_load_dwordx2 s[42:43], s[0:1], 0x128
	v_ashrrev_i32_e32 v35, 31, v34
	s_mov_b32 s17, 0x800000
	s_waitcnt lgkmcnt(0)
	v_lshl_add_u64 v[2:3], v[34:35], 2, s[42:43]
	s_mov_b32 s98, 0x20000
	s_mov_b32 s99, 0
	v_lshl_add_u64 v[2:3], v[2:3], 0, s[98:99]
	s_mov_b32 s98, 0x20400
	s_mov_b32 s99, 0
	global_load_dword v204, v[2:3], off
	v_lshl_add_u64 v[2:3], v[2:3], 0, s[98:99]
	global_load_dword v205, v[2:3], off
	v_lshl_add_u64 v[2:3], v[2:3], 0, s[98:99]
	global_load_dword v206, v[2:3], off
	v_lshl_add_u64 v[2:3], v[2:3], 0, s[98:99]
	global_load_dword v207, v[2:3], off
	v_lshl_add_u64 v[2:3], v[2:3], 0, s[98:99]
	global_load_dword v208, v[2:3], off
	v_lshl_add_u64 v[2:3], v[2:3], 0, s[98:99]
	global_load_dword v209, v[2:3], off
	v_lshl_add_u64 v[2:3], v[2:3], 0, s[98:99]
	global_load_dword v210, v[2:3], off
	v_lshl_add_u64 v[2:3], v[2:3], 0, s[98:99]
	global_load_dword v211, v[2:3], off
	v_lshl_add_u64 v[2:3], v[2:3], 0, s[98:99]
	global_load_dword v212, v[2:3], off
	v_lshl_add_u64 v[2:3], v[2:3], 0, s[98:99]
	global_load_dword v213, v[2:3], off
	v_lshl_add_u64 v[2:3], v[2:3], 0, s[98:99]
	global_load_dword v214, v[2:3], off
	v_lshl_add_u64 v[2:3], v[2:3], 0, s[98:99]
	global_load_dword v215, v[2:3], off
	v_lshl_add_u64 v[2:3], v[2:3], 0, s[98:99]
	global_load_dword v216, v[2:3], off
	v_lshl_add_u64 v[2:3], v[2:3], 0, s[98:99]
	global_load_dword v217, v[2:3], off
	v_lshl_add_u64 v[2:3], v[2:3], 0, s[98:99]
	global_load_dword v218, v[2:3], off
	v_lshl_add_u64 v[2:3], v[2:3], 0, s[98:99]
	global_load_dword v219, v[2:3], off
	s_waitcnt vmcnt(0)
	v_add_f32_e32 v0, 0, v204
	v_add_f32_e32 v0, v0, v205
	v_add_f32_e32 v0, v0, v206
	v_add_f32_e32 v0, v0, v207
	v_add_f32_e32 v0, v0, v208
	v_add_f32_e32 v0, v0, v209
	v_add_f32_e32 v0, v0, v210
	v_add_f32_e32 v0, v0, v211
	v_add_f32_e32 v0, v0, v212
	v_add_f32_e32 v0, v0, v213
	v_add_f32_e32 v0, v0, v214
	v_add_f32_e32 v0, v0, v215
	v_add_f32_e32 v0, v0, v216
	v_add_f32_e32 v0, v0, v217
	v_add_f32_e32 v0, v0, v218
	v_add_f32_e32 v0, v0, v219
	v_fmamk_f32 v0, v0, 0x3a800000, v180
	v_cmp_gt_f32_e32 vcc, s17, v0
	v_mul_f32_e32 v2, 0x4b800000, v0
	s_nop 0
	v_cndmask_b32_e32 v0, v0, v2, vcc
	v_rsq_f32_e32 v0, v0
	s_nop 0
	v_mul_f32_e32 v2, 0x45800000, v0
	v_cndmask_b32_e32 v35, v0, v2, vcc
